# st11 + write-through (sc1) stores for the P3 y rows
# baseline (speedup 1.0000x reference)
.Lp3_nopf:
	v_mov_b64_e32 v[46:47], s[14:15]
	v_and_b32_e32 v97, 0xffff0000, v54
	v_and_b32_e32 v96, 0xffff0000, v58
	v_and_b32_e32 v45, 0xffff0000, v56
	v_lshlrev_b32_e32 v44, 16, v56
	v_and_b32_e32 v49, 0xffff0000, v57
	v_and_b32_e32 v113, 0xffff0000, v70
	v_and_b32_e32 v112, 0xffff0000, v74
	v_lshlrev_b32_e32 v48, 16, v57
	v_and_b32_e32 v57, 0xffff0000, v60
	v_lshlrev_b32_e32 v56, 16, v60
	v_lshlrev_b32_e32 v87, 16, v54
	v_lshlrev_b32_e32 v86, 16, v58
	v_lshlrev_b32_e32 v99, 16, v55
	v_lshlrev_b32_e32 v98, 16, v59
	v_and_b32_e32 v55, 0xffff0000, v55
	v_and_b32_e32 v54, 0xffff0000, v59
	v_and_b32_e32 v59, 0xffff0000, v61
	v_lshlrev_b32_e32 v58, 16, v61
	v_and_b32_e32 v61, 0xffff0000, v64
	v_lshlrev_b32_e32 v60, 16, v64
	v_and_b32_e32 v101, 0xffff0000, v65
	v_lshlrev_b32_e32 v100, 16, v65
	v_and_b32_e32 v65, 0xffff0000, v68
	v_lshlrev_b32_e32 v64, 16, v68
	v_lshlrev_b32_e32 v103, 16, v62
	v_lshlrev_b32_e32 v102, 16, v66
	v_and_b32_e32 v109, 0xffff0000, v62
	v_and_b32_e32 v108, 0xffff0000, v66
	v_lshlrev_b32_e32 v110, 16, v67
	v_and_b32_e32 v62, 0xffff0000, v67
	v_and_b32_e32 v67, 0xffff0000, v69
	v_lshlrev_b32_e32 v66, 16, v69
	v_and_b32_e32 v69, 0xffff0000, v72
	v_lshlrev_b32_e32 v68, 16, v72
	v_and_b32_e32 v105, 0xffff0000, v73
	v_lshlrev_b32_e32 v104, 16, v73
	v_and_b32_e32 v73, 0xffff0000, v76
	v_lshlrev_b32_e32 v72, 16, v76
	v_lshlrev_b32_e32 v107, 16, v70
	v_lshlrev_b32_e32 v106, 16, v74
	v_lshlrev_b32_e32 v119, 16, v71
	v_lshlrev_b32_e32 v118, 16, v75
	v_and_b32_e32 v71, 0xffff0000, v71
	v_and_b32_e32 v70, 0xffff0000, v75
	v_and_b32_e32 v75, 0xffff0000, v77
	v_lshlrev_b32_e32 v74, 16, v77
	v_and_b32_e32 v77, 0xffff0000, v80
	v_lshlrev_b32_e32 v76, 16, v80
	v_and_b32_e32 v125, 0xffff0000, v78
	v_and_b32_e32 v124, 0xffff0000, v82
	v_pk_fma_f32 v[140:141], v[10:11], v[112:113], v[96:97]
	v_and_b32_e32 v121, 0xffff0000, v81
	v_lshlrev_b32_e32 v120, 16, v81
	v_lshlrev_b32_e32 v123, 16, v78
	v_lshlrev_b32_e32 v122, 16, v82
	s_waitcnt lgkmcnt(0)
	v_pk_fma_f32 v[134:135], v[16:17], v[104:105], v[48:49]
	v_pk_fma_f32 v[130:131], v[14:15], v[72:73], v[56:57]
	v_pk_fma_f32 v[138:139], v[36:37], v[106:107], v[86:87]
	v_pk_fma_f32 v[144:145], v[34:35], v[70:71], v[54:55]
	v_pk_fma_f32 v[132:133], v[16:17], v[74:75], v[58:59]
	v_pk_fma_f32 v[104:105], v[14:15], v[76:77], v[60:61]
	v_pk_fma_f32 v[108:109], v[10:11], v[124:125], v[108:109]
	v_lshlrev_b32_e32 v76, 16, v90
	v_and_b32_e32 v74, 0xffff0000, v90
	v_lshlrev_b32_e32 v72, 16, v91
	v_and_b32_e32 v70, 0xffff0000, v91
	v_pk_mul_f32 v[90:91], v[140:141], v[140:141]
	v_lshlrev_b32_e32 v111, 16, v63
	v_and_b32_e32 v63, 0xffff0000, v63
	v_and_b32_e32 v81, 0xffff0000, v84
	v_lshlrev_b32_e32 v80, 16, v84
	v_lshlrev_b32_e32 v127, 16, v79
	v_lshlrev_b32_e32 v126, 16, v83
	v_and_b32_e32 v79, 0xffff0000, v79
	v_and_b32_e32 v78, 0xffff0000, v83
	v_and_b32_e32 v83, 0xffff0000, v85
	v_lshlrev_b32_e32 v82, 16, v85
	v_pk_fma_f32 v[136:137], v[14:15], v[68:69], v[44:45]
	v_pk_fma_f32 v[142:143], v[12:13], v[118:119], v[98:99]
	v_pk_fma_f32 v[86:87], v[16:17], v[120:121], v[100:101]
	v_pk_fma_f32 v[106:107], v[36:37], v[122:123], v[102:103]
	v_pk_mul_f32 v[100:101], v[108:109], v[108:109]
	v_pk_fma_f32 v[120:121], v[138:139], v[138:139], v[90:91]
	v_pk_fma_f32 v[44:45], v[14:15], v[80:81], v[64:65]
	v_pk_fma_f32 v[110:111], v[12:13], v[126:127], v[110:111]
	v_pk_fma_f32 v[112:113], v[34:35], v[78:79], v[62:63]
	v_pk_fma_f32 v[68:69], v[16:17], v[82:83], v[66:67]
	v_lshlrev_b32_e32 v84, 16, v88
	v_and_b32_e32 v82, 0xffff0000, v88
	v_lshlrev_b32_e32 v80, 16, v89
	v_and_b32_e32 v78, 0xffff0000, v89
	v_pk_mul_f32 v[158:159], v[136:137], v[136:137]
	v_pk_mul_f32 v[88:89], v[130:131], v[130:131]
	v_pk_fma_f32 v[122:123], v[106:107], v[106:107], v[100:101]
	v_pk_fma_f32 v[174:175], v[142:143], v[142:143], v[120:121]
	v_pk_mul_f32 v[162:163], v[104:105], v[104:105]
	v_pk_mul_f32 v[98:99], v[44:45], v[44:45]
	v_pk_mul_f32 v[118:119], v[68:69], v[68:69]
	v_mov_b32_e32 v166, v88
	v_mov_b32_e32 v167, v158
	v_pk_fma_f32 v[176:177], v[110:111], v[110:111], v[122:123]
	v_lshlrev_b32_e32 v128, 16, v154
	v_and_b32_e32 v126, 0xffff0000, v154
	v_lshlrev_b32_e32 v124, 16, v155
	v_and_b32_e32 v122, 0xffff0000, v155
	v_pk_fma_f32 v[154:155], v[144:145], v[144:145], v[174:175]
	v_pk_mul_f32 v[160:161], v[134:135], v[134:135]
	v_pk_mul_f32 v[96:97], v[132:133], v[132:133]
	v_lshlrev_b32_e32 v66, 16, v92
	v_and_b32_e32 v64, 0xffff0000, v92
	v_lshlrev_b32_e32 v58, 16, v94
	v_and_b32_e32 v56, 0xffff0000, v94
	v_mov_b32_e32 v168, v98
	v_mov_b32_e32 v169, v162
	v_mov_b32_e32 v158, v89
	v_lshlrev_b32_e32 v102, 16, v114
	v_and_b32_e32 v100, 0xffff0000, v114
	v_lshlrev_b32_e32 v94, 16, v116
	v_and_b32_e32 v92, 0xffff0000, v116
	v_mov_b32_e32 v172, v118
	v_lshlrev_b32_e32 v120, 16, v156
	v_and_b32_e32 v118, 0xffff0000, v156
	v_lshlrev_b32_e32 v116, 16, v157
	v_and_b32_e32 v114, 0xffff0000, v157
	v_pk_fma_f32 v[156:157], v[112:113], v[112:113], v[176:177]
	v_pk_add_f32 v[154:155], v[166:167], v[154:155]
	v_pk_mul_f32 v[164:165], v[86:87], v[86:87]
	v_mov_b32_e32 v170, v96
	v_mov_b32_e32 v171, v160
	v_mov_b32_e32 v162, v99
	v_pk_add_f32 v[156:157], v[168:169], v[156:157]
	v_pk_add_f32 v[154:155], v[158:159], v[154:155]
	v_mov_b32_e32 v160, v97
	v_mov_b32_e32 v173, v164
	v_pk_add_f32 v[156:157], v[162:163], v[156:157]
	v_pk_add_f32 v[154:155], v[170:171], v[154:155]
	v_mov_b32_e32 v164, v119
	v_pk_add_f32 v[156:157], v[172:173], v[156:157]
	v_pk_add_f32 v[154:155], v[160:161], v[154:155]
	v_pk_add_f32 v[156:157], v[164:165], v[156:157]
	s_nop 1
	v_add_f32_dpp v154, v154, v154 quad_perm:[1,0,3,2] row_mask:0xf bank_mask:0xf
	v_add_f32_dpp v155, v155, v155 quad_perm:[1,0,3,2] row_mask:0xf bank_mask:0xf
	v_add_f32_dpp v156, v156, v156 quad_perm:[1,0,3,2] row_mask:0xf bank_mask:0xf
	v_add_f32_dpp v157, v157, v157 quad_perm:[1,0,3,2] row_mask:0xf bank_mask:0xf
	v_add_f32_dpp v154, v154, v154 quad_perm:[2,3,0,1] row_mask:0xf bank_mask:0xf
	v_add_f32_dpp v155, v155, v155 quad_perm:[2,3,0,1] row_mask:0xf bank_mask:0xf
	v_add_f32_dpp v156, v156, v156 quad_perm:[2,3,0,1] row_mask:0xf bank_mask:0xf
	v_add_f32_dpp v157, v157, v157 quad_perm:[2,3,0,1] row_mask:0xf bank_mask:0xf
	v_add_f32_dpp v154, v154, v154 row_half_mirror row_mask:0xf bank_mask:0xf
	v_add_f32_dpp v155, v155, v155 row_half_mirror row_mask:0xf bank_mask:0xf
	v_add_f32_dpp v156, v156, v156 row_half_mirror row_mask:0xf bank_mask:0xf
	v_add_f32_dpp v157, v157, v157 row_half_mirror row_mask:0xf bank_mask:0xf
	v_add_f32_dpp v154, v154, v154 row_mirror row_mask:0xf bank_mask:0xf
	v_add_f32_dpp v155, v155, v155 row_mirror row_mask:0xf bank_mask:0xf
	v_add_f32_dpp v156, v156, v156 row_mirror row_mask:0xf bank_mask:0xf
	v_add_f32_dpp v157, v157, v157 row_mirror row_mask:0xf bank_mask:0xf
	v_mov_b32_e32 v158, v154
	v_mov_b32_e32 v159, v155
	v_mov_b32_e32 v160, v156
	v_mov_b32_e32 v161, v157
	v_permlane16_swap_b32 v158, v154
	v_permlane16_swap_b32 v159, v155
	v_permlane16_swap_b32 v160, v156
	v_permlane16_swap_b32 v161, v157
	v_add_f32_e32 v154, v154, v158
	v_add_f32_e32 v155, v155, v159
	v_add_f32_e32 v156, v156, v160
	v_add_f32_e32 v157, v157, v161
	v_mov_b32_e32 v158, v154
	v_mov_b32_e32 v159, v155
	v_mov_b32_e32 v160, v156
	v_mov_b32_e32 v161, v157
	v_permlane32_swap_b32 v158, v154
	v_permlane32_swap_b32 v159, v155
	v_permlane32_swap_b32 v160, v156
	v_permlane32_swap_b32 v161, v157
	v_add_f32_e32 v154, v154, v158
	v_add_f32_e32 v155, v155, v159
	v_add_f32_e32 v156, v156, v160
	v_add_f32_e32 v157, v157, v161
	v_lshlrev_b32_e32 v62, 16, v93
	v_and_b32_e32 v60, 0xffff0000, v93
	v_mul_f32_e32 v49, 0xbfb8aa3b, v66
	v_mul_f32_e32 v55, 0xbfb8aa3b, v64
	v_mul_f32_e32 v57, 0xbfb8aa3b, v62
	v_mul_f32_e32 v59, 0xbfb8aa3b, v60
	v_exp_f32_e32 v49, v49
	v_exp_f32_e32 v55, v55
	v_exp_f32_e32 v57, v57
	v_exp_f32_e32 v59, v59
	v_mul_f32_e32 v2, 0xbfb8aa3b, v84
	v_mul_f32_e32 v4, 0xbfb8aa3b, v82
	v_mul_f32_e32 v6, 0xbfb8aa3b, v80
	v_mul_f32_e32 v8, 0xbfb8aa3b, v78
	v_mul_f32_e32 v26, 0xbfb8aa3b, v76
	v_mul_f32_e32 v28, 0xbfb8aa3b, v74
	v_mul_f32_e32 v30, 0xbfb8aa3b, v72
	v_mul_f32_e32 v32, 0xbfb8aa3b, v70
	v_pk_fma_f32 v[154:155], v[154:155], s[12:13], v[46:47] op_sel_hi:[1,0,0]
	v_exp_f32_e32 v2, v2
	v_exp_f32_e32 v4, v4
	v_exp_f32_e32 v6, v6
	v_exp_f32_e32 v8, v8
	v_exp_f32_e32 v26, v26
	v_exp_f32_e32 v28, v28
	v_exp_f32_e32 v30, v30
	v_exp_f32_e32 v32, v32
	v_add_f32_e32 v153, 1.0, v49
	v_pk_fma_f32 v[46:47], v[156:157], s[12:13], v[46:47] op_sel_hi:[1,0,0]
	v_mul_f32_e32 v49, 0x4b800000, v155
	v_cmp_gt_f32_e64 s[6:7], s15, v155
	v_add_f32_e32 v162, 1.0, v55
	v_add_f32_e32 v163, 1.0, v57
	v_add_f32_e32 v166, 1.0, v59
	v_mul_f32_e32 v55, 0x4b800000, v154
	v_cmp_gt_f32_e32 vcc, s15, v154
	v_mul_f32_e32 v57, 0x4b800000, v47
	v_mul_f32_e32 v59, 0x4b800000, v46
	v_cmp_gt_f32_e64 s[0:1], s15, v46
	v_cmp_gt_f32_e64 s[4:5], s15, v47
	v_cndmask_b32_e64 v49, v155, v49, s[6:7]
	v_lshlrev_b32_e32 v54, 16, v95
	v_and_b32_e32 v48, 0xffff0000, v95
	v_mul_f32_e32 v61, 0xbfb8aa3b, v58
	v_mul_f32_e32 v63, 0xbfb8aa3b, v56
	v_lshlrev_b32_e32 v98, 16, v115
	v_and_b32_e32 v96, 0xffff0000, v115
	v_lshlrev_b32_e32 v90, 16, v117
	v_and_b32_e32 v88, 0xffff0000, v117
	v_cndmask_b32_e32 v55, v154, v55, vcc
	v_cndmask_b32_e64 v47, v47, v57, s[4:5]
	v_cndmask_b32_e64 v46, v46, v59, s[0:1]
	v_rsq_f32_e32 v49, v49
	v_mul_f32_e32 v65, 0xbfb8aa3b, v54
	v_mul_f32_e32 v67, 0xbfb8aa3b, v48
	v_exp_f32_e32 v61, v61
	v_exp_f32_e32 v63, v63
	v_mul_f32_e32 v71, 0xbfb8aa3b, v102
	v_mul_f32_e32 v73, 0xbfb8aa3b, v100
	v_mul_f32_e32 v75, 0xbfb8aa3b, v98
	v_mul_f32_e32 v77, 0xbfb8aa3b, v96
	v_mul_f32_e32 v79, 0xbfb8aa3b, v94
	v_mul_f32_e32 v81, 0xbfb8aa3b, v92
	v_mul_f32_e32 v83, 0xbfb8aa3b, v90
	v_mul_f32_e32 v85, 0xbfb8aa3b, v88
	v_mul_f32_e32 v89, 0xbfb8aa3b, v128
	v_rsq_f32_e32 v55, v55
	v_rsq_f32_e32 v47, v47
	v_rsq_f32_e32 v46, v46
	v_exp_f32_e32 v65, v65
	v_exp_f32_e32 v67, v67
	v_exp_f32_e32 v71, v71
	v_exp_f32_e32 v73, v73
	v_exp_f32_e32 v75, v75
	v_exp_f32_e32 v77, v77
	v_exp_f32_e32 v79, v79
	v_exp_f32_e32 v81, v81
	v_exp_f32_e32 v83, v83
	v_exp_f32_e32 v85, v85
	v_mul_f32_e32 v91, 0xbfb8aa3b, v126
	v_mul_f32_e32 v93, 0xbfb8aa3b, v124
	v_mul_f32_e32 v95, 0xbfb8aa3b, v122
	v_mul_f32_e32 v97, 0xbfb8aa3b, v120
	v_mul_f32_e32 v99, 0xbfb8aa3b, v118
	v_mul_f32_e32 v101, 0xbfb8aa3b, v116
	v_mul_f32_e32 v103, 0xbfb8aa3b, v114
	v_exp_f32_e32 v89, v89
	v_add_f32_e32 v2, 1.0, v2
	v_add_f32_e32 v4, 1.0, v4
	v_add_f32_e32 v115, 1.0, v6
	v_add_f32_e32 v8, 1.0, v8
	v_add_f32_e32 v26, 1.0, v26
	v_add_f32_e32 v117, 1.0, v28
	v_add_f32_e32 v119, 1.0, v30
	v_add_f32_e32 v121, 1.0, v32
	v_exp_f32_e32 v91, v91
	v_exp_f32_e32 v93, v93
	v_exp_f32_e32 v95, v95
	v_exp_f32_e32 v97, v97
	v_exp_f32_e32 v99, v99
	v_exp_f32_e32 v101, v101
	v_exp_f32_e32 v103, v103
	v_rcp_f32_e32 v32, v2
	v_rcp_f32_e32 v6, v4
	v_rcp_f32_e32 v30, v115
	v_rcp_f32_e32 v8, v8
	v_rcp_f32_e32 v28, v26
	v_rcp_f32_e32 v2, v117
	v_rcp_f32_e32 v26, v119
	v_rcp_f32_e32 v4, v121
	v_mul_f32_e32 v57, 0x45800000, v49
	v_add_f32_e32 v167, 1.0, v61
	v_add_f32_e32 v168, 1.0, v63
	v_mul_f32_e32 v59, 0x45800000, v55
	v_mul_f32_e32 v61, 0x45800000, v47
	v_mul_f32_e32 v63, 0x45800000, v46
	v_cndmask_b32_e64 v49, v49, v57, s[6:7]
	v_add_f32_e32 v169, 1.0, v65
	v_add_f32_e32 v170, 1.0, v67
	v_add_f32_e32 v171, 1.0, v71
	v_add_f32_e32 v172, 1.0, v73
	v_add_f32_e32 v173, 1.0, v75
	v_add_f32_e32 v174, 1.0, v77
	v_add_f32_e32 v175, 1.0, v79
	v_add_f32_e32 v176, 1.0, v81
	v_add_f32_e32 v177, 1.0, v83
	v_add_f32_e32 v178, 1.0, v85
	v_add_f32_e32 v164, 1.0, v89
	v_cndmask_b32_e32 v89, v55, v59, vcc
	v_cndmask_b32_e64 v47, v47, v61, s[4:5]
	v_cndmask_b32_e64 v46, v46, v63, s[0:1]
	v_mul_f32_e32 v85, v139, v49
	v_mul_f32_e32 v83, v141, v49
	v_mul_f32_e32 v81, v143, v49
	v_mul_f32_e32 v79, v145, v49
	v_mul_f32_e32 v77, v136, v49
	v_mul_f32_e32 v75, v137, v49
	v_mul_f32_e32 v73, v134, v49
	v_mul_f32_e32 v71, v135, v49
	v_add_f32_e32 v165, 1.0, v91
	v_add_f32_e32 v179, 1.0, v93
	v_add_f32_e32 v180, 1.0, v95
	v_add_f32_e32 v181, 1.0, v97
	v_add_f32_e32 v182, 1.0, v99
	v_add_f32_e32 v183, 1.0, v101
	v_add_f32_e32 v184, 1.0, v103
	v_mul_f32_e32 v67, v138, v89
	v_mul_f32_e32 v65, v140, v89
	v_mul_f32_e32 v63, v142, v89
	v_mul_f32_e32 v61, v144, v89
	v_mul_f32_e32 v59, v130, v89
	v_mul_f32_e32 v57, v131, v89
	v_mul_f32_e32 v55, v132, v89
	v_mul_f32_e32 v49, v133, v89
	v_mul_f32_e32 v103, v107, v47
	v_mul_f32_e32 v101, v109, v47
	v_mul_f32_e32 v99, v111, v47
	v_mul_f32_e32 v97, v113, v47
	v_mul_f32_e32 v95, v104, v47
	v_mul_f32_e32 v93, v105, v47
	v_mul_f32_e32 v91, v86, v47
	v_mul_f32_e32 v89, v87, v47
	v_mul_f32_e32 v129, v106, v46
	v_mul_f32_e32 v127, v108, v46
	v_mul_f32_e32 v125, v110, v46
	v_mul_f32_e32 v123, v112, v46
	v_mul_f32_e32 v121, v44, v46
	v_mul_f32_e32 v119, v45, v46
	v_mul_f32_e32 v117, v68, v46
	v_mul_f32_e32 v115, v69, v46
	v_pk_mul_f32 v[44:45], v[32:33], v[84:85]
	v_pk_mul_f32 v[46:47], v[6:7], v[82:83]
	v_pk_mul_f32 v[68:69], v[30:31], v[80:81]
	v_pk_mul_f32 v[78:79], v[8:9], v[78:79]
	v_pk_mul_f32 v[76:77], v[28:29], v[76:77]
	v_pk_mul_f32 v[74:75], v[2:3], v[74:75]
	v_pk_mul_f32 v[72:73], v[26:27], v[72:73]
	v_pk_mul_f32 v[70:71], v[4:5], v[70:71]
	v_rcp_f32_e32 v32, v153
	v_rcp_f32_e32 v6, v162
	v_rcp_f32_e32 v30, v163
	v_rcp_f32_e32 v8, v166
	v_rcp_f32_e32 v28, v167
	v_rcp_f32_e32 v2, v168
	v_rcp_f32_e32 v26, v169
	v_rcp_f32_e32 v4, v170
	v_mul_f32_e32 v44, v44, v45
	v_mul_f32_e32 v45, v46, v47
	v_mul_f32_e32 v46, v68, v69
	v_mul_f32_e32 v47, v78, v79
	v_mul_f32_e32 v68, v76, v77
	v_mul_f32_e32 v69, v74, v75
	v_mul_f32_e32 v72, v72, v73
	v_mul_f32_e32 v70, v70, v71
	v_cvt_pk_bf16_f32 v44, v44, v45
	v_cvt_pk_bf16_f32 v45, v46, v47
	v_cvt_pk_bf16_f32 v46, v68, v69
	v_cvt_pk_bf16_f32 v47, v72, v70
	global_store_dwordx4 v[50:51], v[44:47], off offset:-4096 sc1
	v_pk_mul_f32 v[62:63], v[30:31], v[62:63]
	v_pk_mul_f32 v[60:61], v[8:9], v[60:61]
	v_pk_mul_f32 v[44:45], v[32:33], v[66:67]
	v_pk_mul_f32 v[46:47], v[6:7], v[64:65]
	v_pk_mul_f32 v[58:59], v[28:29], v[58:59]
	v_pk_mul_f32 v[56:57], v[2:3], v[56:57]
	v_pk_mul_f32 v[54:55], v[26:27], v[54:55]
	v_pk_mul_f32 v[48:49], v[4:5], v[48:49]
	v_rcp_f32_e32 v32, v171
	v_rcp_f32_e32 v6, v172
	v_rcp_f32_e32 v30, v173
	v_rcp_f32_e32 v8, v174
	v_rcp_f32_e32 v28, v175
	v_rcp_f32_e32 v2, v176
	v_rcp_f32_e32 v26, v177
	v_rcp_f32_e32 v4, v178
	v_mul_f32_e32 v44, v44, v45
	v_mul_f32_e32 v45, v46, v47
	v_mul_f32_e32 v46, v62, v63
	v_mul_f32_e32 v47, v60, v61
	v_mul_f32_e32 v58, v58, v59
	v_mul_f32_e32 v56, v56, v57
	v_mul_f32_e32 v54, v54, v55
	v_mul_f32_e32 v48, v48, v49
	v_cvt_pk_bf16_f32 v44, v44, v45
	v_cvt_pk_bf16_f32 v45, v46, v47
	v_cvt_pk_bf16_f32 v46, v58, v56
	v_cvt_pk_bf16_f32 v47, v54, v48
	global_store_dwordx4 v[52:53], v[44:47], off offset:2048 sc1
	v_pk_mul_f32 v[48:49], v[30:31], v[98:99]
	v_pk_mul_f32 v[52:53], v[8:9], v[96:97]
	v_pk_mul_f32 v[44:45], v[32:33], v[102:103]
	v_pk_mul_f32 v[46:47], v[6:7], v[100:101]
	v_pk_mul_f32 v[54:55], v[28:29], v[94:95]
	v_pk_mul_f32 v[56:57], v[2:3], v[92:93]
	v_pk_mul_f32 v[58:59], v[26:27], v[90:91]
	v_pk_mul_f32 v[60:61], v[4:5], v[88:89]
	v_rcp_f32_e32 v32, v164
	v_rcp_f32_e32 v6, v165
	v_rcp_f32_e32 v30, v179
	v_rcp_f32_e32 v8, v180
	v_rcp_f32_e32 v28, v181
	v_rcp_f32_e32 v2, v182
	v_rcp_f32_e32 v26, v183
	v_rcp_f32_e32 v4, v184
	v_mul_f32_e32 v44, v44, v45
	v_mul_f32_e32 v45, v46, v47
	v_mul_f32_e32 v46, v48, v49
	v_mul_f32_e32 v47, v52, v53
	v_mul_f32_e32 v48, v54, v55
	v_mul_f32_e32 v49, v56, v57
	v_mul_f32_e32 v52, v58, v59
	v_mul_f32_e32 v53, v60, v61
	v_cvt_pk_bf16_f32 v44, v44, v45
	v_cvt_pk_bf16_f32 v45, v46, v47
	v_cvt_pk_bf16_f32 v46, v48, v49
	v_cvt_pk_bf16_f32 v47, v52, v53
	global_store_dwordx4 v[50:51], v[44:47], off sc1
	v_pk_mul_f32 v[48:49], v[30:31], v[124:125]
	v_pk_mul_f32 v[52:53], v[8:9], v[122:123]
	v_pk_mul_f32 v[44:45], v[32:33], v[128:129]
	v_pk_mul_f32 v[46:47], v[6:7], v[126:127]
	v_pk_mul_f32 v[54:55], v[28:29], v[120:121]
	v_pk_mul_f32 v[56:57], v[2:3], v[118:119]
	v_pk_mul_f32 v[58:59], v[26:27], v[116:117]
	v_pk_mul_f32 v[60:61], v[4:5], v[114:115]
	v_mul_f32_e32 v2, v44, v45
	v_mul_f32_e32 v4, v46, v47
	v_mul_f32_e32 v6, v48, v49
	v_mul_f32_e32 v8, v52, v53
	v_mul_f32_e32 v26, v54, v55
	v_mul_f32_e32 v28, v56, v57
	v_mul_f32_e32 v30, v58, v59
	v_mul_f32_e32 v32, v60, v61
	v_cvt_pk_bf16_f32 v44, v2, v4
	v_cvt_pk_bf16_f32 v45, v6, v8
	v_cvt_pk_bf16_f32 v46, v26, v28
	v_cvt_pk_bf16_f32 v47, v30, v32
	global_store_dwordx4 v[50:51], v[44:47], off offset:2048 sc1
	s_cbranch_scc1 .Lp3_done
	s_waitcnt vmcnt(4)
	v_mov_b64_e32 v[54:55], v[188:189]
	v_mov_b64_e32 v[56:57], v[190:191]
	v_mov_b64_e32 v[58:59], v[192:193]
	v_mov_b64_e32 v[60:61], v[194:195]
	v_mov_b64_e32 v[62:63], v[196:197]
	v_mov_b64_e32 v[64:65], v[198:199]
	v_mov_b64_e32 v[66:67], v[200:201]
	v_mov_b64_e32 v[68:69], v[202:203]
	v_mov_b64_e32 v[70:71], v[204:205]
	v_mov_b64_e32 v[72:73], v[206:207]
	v_mov_b64_e32 v[74:75], v[208:209]
	v_mov_b64_e32 v[76:77], v[210:211]
	v_mov_b64_e32 v[78:79], v[212:213]
	v_mov_b64_e32 v[80:81], v[214:215]
	v_mov_b64_e32 v[82:83], v[216:217]
	v_mov_b64_e32 v[84:85], v[218:219]
	v_mov_b64_e32 v[88:89], v[220:221]
	v_mov_b64_e32 v[90:91], v[222:223]
	v_mov_b64_e32 v[92:93], v[224:225]
	v_mov_b64_e32 v[94:95], v[226:227]
	v_mov_b64_e32 v[114:115], v[228:229]
	v_mov_b64_e32 v[116:117], v[230:231]
	v_mov_b64_e32 v[154:155], v[232:233]
	v_mov_b64_e32 v[156:157], v[234:235]
	v_mov_b64_e32 v[50:51], v[236:237]
	v_mov_b64_e32 v[52:53], v[238:239]
	s_branch .LBB0_293
